# phase-4 q-up rope tiles: cos/sin loads all in flight, rotation then wave-private LDS transpose and row-contiguous stores (replaces per-row dependent load/store chain)
# speedup vs baseline: 1.0079x; 1.0079x over previous
.Lp4q_rope:
	s_nop 15
	v_lshl_add_u64 v[66:67], v[66:67], 3, v[160:161]
	v_mad_u64_u32 v[70:71], s[32:33], v66, s38, v[152:153]
	v_mad_i32_i24 v71, v67, s38, v71
	s_nop 0
	v_readfirstlane_b32 s32, v70
	v_readfirstlane_b32 s33, v71
	v_readfirstlane_b32 s30, v186
	s_lshr_b32 s30, s30, 6
	s_mul_i32 s30, s30, 0x2400
	v_and_b32_e32 v90, 31, v186
	v_bfe_u32 v91, v186, 5, 1
	v_mul_u32_u24_e32 v91, 576, v91
	v_lshl_add_u32 v90, v90, 1, v91
	v_add_u32_e32 v90, s30, v90
	v_and_b32_e32 v92, 63, v186
	v_lshrrev_b32_e32 v93, 3, v92
	v_and_b32_e32 v92, 7, v92
	v_mul_u32_u24_e32 v94, 144, v93
	v_lshl_add_u32 v94, v92, 4, v94
	v_add_u32_e32 v94, s30, v94
	v_mul_u32_u24_e32 v95, 1536, v93
	v_lshl_add_u32 v95, v92, 4, v95
	v_lshrrev_b32_e32 v91, 2, v92
	v_and_b32_e32 v92, 3, v92
	v_mul_u32_u24_e32 v95, 1536, v93
	v_mul_u32_u24_e32 v91, 192, v91
	v_add_u32_e32 v95, v95, v91
	v_lshl_add_u32 v95, v92, 4, v95
	v_or_b32_e32 v158, v68, v164
	v_lshl_or_b32 v158, v158, 4, v165
	v_lshlrev_b32_e32 v158, 2, v158
	global_load_dword v219, v158, s[10:11]
	global_load_dword v128, v158, s[14:15]
	global_load_dword v220, v158, s[10:11] offset:64
	global_load_dword v129, v158, s[14:15] offset:64
	global_load_dword v221, v158, s[10:11] offset:128
	global_load_dword v130, v158, s[14:15] offset:128
	global_load_dword v222, v158, s[10:11] offset:192
	global_load_dword v131, v158, s[14:15] offset:192
	global_load_dword v223, v158, s[10:11] offset:512
	global_load_dword v132, v158, s[14:15] offset:512
	global_load_dword v224, v158, s[10:11] offset:576
	global_load_dword v133, v158, s[14:15] offset:576
	global_load_dword v225, v158, s[10:11] offset:640
	global_load_dword v134, v158, s[14:15] offset:640
	global_load_dword v226, v158, s[10:11] offset:704
	global_load_dword v135, v158, s[14:15] offset:704
	global_load_dword v227, v158, s[10:11] offset:1024
	global_load_dword v136, v158, s[14:15] offset:1024
	global_load_dword v228, v158, s[10:11] offset:1088
	global_load_dword v137, v158, s[14:15] offset:1088
	global_load_dword v229, v158, s[10:11] offset:1152
	global_load_dword v138, v158, s[14:15] offset:1152
	global_load_dword v230, v158, s[10:11] offset:1216
	global_load_dword v139, v158, s[14:15] offset:1216
	global_load_dword v231, v158, s[10:11] offset:1536
	global_load_dword v140, v158, s[14:15] offset:1536
	global_load_dword v232, v158, s[10:11] offset:1600
	global_load_dword v141, v158, s[14:15] offset:1600
	global_load_dword v233, v158, s[10:11] offset:1664
	global_load_dword v142, v158, s[14:15] offset:1664
	global_load_dword v234, v158, s[10:11] offset:1728
	global_load_dword v143, v158, s[14:15] offset:1728
	global_load_dword v235, v158, s[10:11] offset:2048
	global_load_dword v84, v158, s[14:15] offset:2048
	global_load_dword v236, v158, s[10:11] offset:2112
	global_load_dword v85, v158, s[14:15] offset:2112
	global_load_dword v237, v158, s[10:11] offset:2176
	global_load_dword v86, v158, s[14:15] offset:2176
	global_load_dword v238, v158, s[10:11] offset:2240
	global_load_dword v87, v158, s[14:15] offset:2240
	global_load_dword v239, v158, s[10:11] offset:2560
	global_load_dword v88, v158, s[14:15] offset:2560
	global_load_dword v240, v158, s[10:11] offset:2624
	global_load_dword v89, v158, s[14:15] offset:2624
	global_load_dword v241, v158, s[10:11] offset:2688
	global_load_dword v74, v158, s[14:15] offset:2688
	global_load_dword v242, v158, s[10:11] offset:2752
	global_load_dword v75, v158, s[14:15] offset:2752
	global_load_dword v243, v158, s[10:11] offset:3072
	global_load_dword v76, v158, s[14:15] offset:3072
	global_load_dword v244, v158, s[10:11] offset:3136
	global_load_dword v77, v158, s[14:15] offset:3136
	global_load_dword v245, v158, s[10:11] offset:3200
	global_load_dword v78, v158, s[14:15] offset:3200
	global_load_dword v246, v158, s[10:11] offset:3264
	global_load_dword v80, v158, s[14:15] offset:3264
	global_load_dword v247, v158, s[10:11] offset:3584
	global_load_dword v81, v158, s[14:15] offset:3584
	global_load_dword v248, v158, s[10:11] offset:3648
	global_load_dword v82, v158, s[14:15] offset:3648
	global_load_dword v249, v158, s[10:11] offset:3712
	global_load_dword v156, v158, s[14:15] offset:3712
	global_load_dword v250, v158, s[10:11] offset:3776
	global_load_dword v157, v158, s[14:15] offset:3776
	v_and_b32_e32 v159, 63, v186
	v_xor_b32_e32 v159, 16, v159
	v_lshlrev_b32_e32 v159, 2, v159
	ds_bpermute_b32 v188, v159, v32
	ds_bpermute_b32 v189, v159, v33
	ds_bpermute_b32 v192, v159, v34
	ds_bpermute_b32 v193, v159, v35
	ds_bpermute_b32 v200, v159, v36
	ds_bpermute_b32 v201, v159, v37
	ds_bpermute_b32 v202, v159, v38
	ds_bpermute_b32 v203, v159, v39
	s_waitcnt vmcnt(0) lgkmcnt(0)
	v_mul_f32_e32 v188, v128, v188
	v_cndmask_b32_e64 v188, v188, -v188, s[4:5]
	v_fma_f32 v32, v32, v219, v188
	v_mul_f32_e32 v189, v129, v189
	v_cndmask_b32_e64 v189, v189, -v189, s[4:5]
	v_fma_f32 v33, v33, v220, v189
	v_mul_f32_e32 v192, v130, v192
	v_cndmask_b32_e64 v192, v192, -v192, s[4:5]
	v_fma_f32 v34, v34, v221, v192
	v_mul_f32_e32 v193, v131, v193
	v_cndmask_b32_e64 v193, v193, -v193, s[4:5]
	v_fma_f32 v35, v35, v222, v193
	v_mul_f32_e32 v200, v132, v200
	v_cndmask_b32_e64 v200, v200, -v200, s[4:5]
	v_fma_f32 v36, v36, v223, v200
	v_mul_f32_e32 v201, v133, v201
	v_cndmask_b32_e64 v201, v201, -v201, s[4:5]
	v_fma_f32 v37, v37, v224, v201
	v_mul_f32_e32 v202, v134, v202
	v_cndmask_b32_e64 v202, v202, -v202, s[4:5]
	v_fma_f32 v38, v38, v225, v202
	v_mul_f32_e32 v203, v135, v203
	v_cndmask_b32_e64 v203, v203, -v203, s[4:5]
	v_fma_f32 v39, v39, v226, v203
	ds_bpermute_b32 v188, v159, v40
	ds_bpermute_b32 v189, v159, v41
	ds_bpermute_b32 v192, v159, v42
	ds_bpermute_b32 v193, v159, v43
	ds_bpermute_b32 v200, v159, v44
	ds_bpermute_b32 v201, v159, v45
	ds_bpermute_b32 v202, v159, v46
	ds_bpermute_b32 v203, v159, v47
	s_waitcnt lgkmcnt(0)
	v_mul_f32_e32 v188, v136, v188
	v_cndmask_b32_e64 v188, v188, -v188, s[4:5]
	v_fma_f32 v40, v40, v227, v188
	v_mul_f32_e32 v189, v137, v189
	v_cndmask_b32_e64 v189, v189, -v189, s[4:5]
	v_fma_f32 v41, v41, v228, v189
	v_mul_f32_e32 v192, v138, v192
	v_cndmask_b32_e64 v192, v192, -v192, s[4:5]
	v_fma_f32 v42, v42, v229, v192
	v_mul_f32_e32 v193, v139, v193
	v_cndmask_b32_e64 v193, v193, -v193, s[4:5]
	v_fma_f32 v43, v43, v230, v193
	v_mul_f32_e32 v200, v140, v200
	v_cndmask_b32_e64 v200, v200, -v200, s[4:5]
	v_fma_f32 v44, v44, v231, v200
	v_mul_f32_e32 v201, v141, v201
	v_cndmask_b32_e64 v201, v201, -v201, s[4:5]
	v_fma_f32 v45, v45, v232, v201
	v_mul_f32_e32 v202, v142, v202
	v_cndmask_b32_e64 v202, v202, -v202, s[4:5]
	v_fma_f32 v46, v46, v233, v202
	v_mul_f32_e32 v203, v143, v203
	v_cndmask_b32_e64 v203, v203, -v203, s[4:5]
	v_fma_f32 v47, v47, v234, v203
	ds_bpermute_b32 v188, v159, v48
	ds_bpermute_b32 v189, v159, v49
	ds_bpermute_b32 v192, v159, v50
	ds_bpermute_b32 v193, v159, v51
	ds_bpermute_b32 v200, v159, v52
	ds_bpermute_b32 v201, v159, v53
	ds_bpermute_b32 v202, v159, v54
	ds_bpermute_b32 v203, v159, v55
	s_waitcnt lgkmcnt(0)
	v_mul_f32_e32 v188, v128, v188
	v_cndmask_b32_e64 v188, v188, -v188, s[4:5]
	v_fma_f32 v48, v48, v219, v188
	v_mul_f32_e32 v189, v129, v189
	v_cndmask_b32_e64 v189, v189, -v189, s[4:5]
	v_fma_f32 v49, v49, v220, v189
	v_mul_f32_e32 v192, v130, v192
	v_cndmask_b32_e64 v192, v192, -v192, s[4:5]
	v_fma_f32 v50, v50, v221, v192
	v_mul_f32_e32 v193, v131, v193
	v_cndmask_b32_e64 v193, v193, -v193, s[4:5]
	v_fma_f32 v51, v51, v222, v193
	v_mul_f32_e32 v200, v132, v200
	v_cndmask_b32_e64 v200, v200, -v200, s[4:5]
	v_fma_f32 v52, v52, v223, v200
	v_mul_f32_e32 v201, v133, v201
	v_cndmask_b32_e64 v201, v201, -v201, s[4:5]
	v_fma_f32 v53, v53, v224, v201
	v_mul_f32_e32 v202, v134, v202
	v_cndmask_b32_e64 v202, v202, -v202, s[4:5]
	v_fma_f32 v54, v54, v225, v202
	v_mul_f32_e32 v203, v135, v203
	v_cndmask_b32_e64 v203, v203, -v203, s[4:5]
	v_fma_f32 v55, v55, v226, v203
	ds_bpermute_b32 v188, v159, v56
	ds_bpermute_b32 v189, v159, v57
	ds_bpermute_b32 v192, v159, v58
	ds_bpermute_b32 v193, v159, v59
	ds_bpermute_b32 v200, v159, v60
	ds_bpermute_b32 v201, v159, v61
	ds_bpermute_b32 v202, v159, v62
	ds_bpermute_b32 v203, v159, v63
	s_waitcnt lgkmcnt(0)
	v_mul_f32_e32 v188, v136, v188
	v_cndmask_b32_e64 v188, v188, -v188, s[4:5]
	v_fma_f32 v56, v56, v227, v188
	v_mul_f32_e32 v189, v137, v189
	v_cndmask_b32_e64 v189, v189, -v189, s[4:5]
	v_fma_f32 v57, v57, v228, v189
	v_mul_f32_e32 v192, v138, v192
	v_cndmask_b32_e64 v192, v192, -v192, s[4:5]
	v_fma_f32 v58, v58, v229, v192
	v_mul_f32_e32 v193, v139, v193
	v_cndmask_b32_e64 v193, v193, -v193, s[4:5]
	v_fma_f32 v59, v59, v230, v193
	v_mul_f32_e32 v200, v140, v200
	v_cndmask_b32_e64 v200, v200, -v200, s[4:5]
	v_fma_f32 v60, v60, v231, v200
	v_mul_f32_e32 v201, v141, v201
	v_cndmask_b32_e64 v201, v201, -v201, s[4:5]
	v_fma_f32 v61, v61, v232, v201
	v_mul_f32_e32 v202, v142, v202
	v_cndmask_b32_e64 v202, v202, -v202, s[4:5]
	v_fma_f32 v62, v62, v233, v202
	v_mul_f32_e32 v203, v143, v203
	v_cndmask_b32_e64 v203, v203, -v203, s[4:5]
	v_fma_f32 v63, v63, v234, v203
	ds_bpermute_b32 v188, v159, v16
	ds_bpermute_b32 v189, v159, v17
	ds_bpermute_b32 v192, v159, v18
	ds_bpermute_b32 v193, v159, v19
	ds_bpermute_b32 v200, v159, v20
	ds_bpermute_b32 v201, v159, v21
	ds_bpermute_b32 v202, v159, v22
	ds_bpermute_b32 v203, v159, v23
	s_waitcnt lgkmcnt(0)
	v_mul_f32_e32 v188, v84, v188
	v_cndmask_b32_e64 v188, v188, -v188, s[4:5]
	v_fma_f32 v16, v16, v235, v188
	v_mul_f32_e32 v189, v85, v189
	v_cndmask_b32_e64 v189, v189, -v189, s[4:5]
	v_fma_f32 v17, v17, v236, v189
	v_mul_f32_e32 v192, v86, v192
	v_cndmask_b32_e64 v192, v192, -v192, s[4:5]
	v_fma_f32 v18, v18, v237, v192
	v_mul_f32_e32 v193, v87, v193
	v_cndmask_b32_e64 v193, v193, -v193, s[4:5]
	v_fma_f32 v19, v19, v238, v193
	v_mul_f32_e32 v200, v88, v200
	v_cndmask_b32_e64 v200, v200, -v200, s[4:5]
	v_fma_f32 v20, v20, v239, v200
	v_mul_f32_e32 v201, v89, v201
	v_cndmask_b32_e64 v201, v201, -v201, s[4:5]
	v_fma_f32 v21, v21, v240, v201
	v_mul_f32_e32 v202, v74, v202
	v_cndmask_b32_e64 v202, v202, -v202, s[4:5]
	v_fma_f32 v22, v22, v241, v202
	v_mul_f32_e32 v203, v75, v203
	v_cndmask_b32_e64 v203, v203, -v203, s[4:5]
	v_fma_f32 v23, v23, v242, v203
	ds_bpermute_b32 v188, v159, v24
	ds_bpermute_b32 v189, v159, v25
	ds_bpermute_b32 v192, v159, v26
	ds_bpermute_b32 v193, v159, v27
	ds_bpermute_b32 v200, v159, v28
	ds_bpermute_b32 v201, v159, v29
	ds_bpermute_b32 v202, v159, v30
	ds_bpermute_b32 v203, v159, v31
	s_waitcnt lgkmcnt(0)
	v_mul_f32_e32 v188, v76, v188
	v_cndmask_b32_e64 v188, v188, -v188, s[4:5]
	v_fma_f32 v24, v24, v243, v188
	v_mul_f32_e32 v189, v77, v189
	v_cndmask_b32_e64 v189, v189, -v189, s[4:5]
	v_fma_f32 v25, v25, v244, v189
	v_mul_f32_e32 v192, v78, v192
	v_cndmask_b32_e64 v192, v192, -v192, s[4:5]
	v_fma_f32 v26, v26, v245, v192
	v_mul_f32_e32 v193, v80, v193
	v_cndmask_b32_e64 v193, v193, -v193, s[4:5]
	v_fma_f32 v27, v27, v246, v193
	v_mul_f32_e32 v200, v81, v200
	v_cndmask_b32_e64 v200, v200, -v200, s[4:5]
	v_fma_f32 v28, v28, v247, v200
	v_mul_f32_e32 v201, v82, v201
	v_cndmask_b32_e64 v201, v201, -v201, s[4:5]
	v_fma_f32 v29, v29, v248, v201
	v_mul_f32_e32 v202, v156, v202
	v_cndmask_b32_e64 v202, v202, -v202, s[4:5]
	v_fma_f32 v30, v30, v249, v202
	v_mul_f32_e32 v203, v157, v203
	v_cndmask_b32_e64 v203, v203, -v203, s[4:5]
	v_fma_f32 v31, v31, v250, v203
	ds_bpermute_b32 v188, v159, v0
	ds_bpermute_b32 v189, v159, v1
	ds_bpermute_b32 v192, v159, v2
	ds_bpermute_b32 v193, v159, v3
	ds_bpermute_b32 v200, v159, v4
	ds_bpermute_b32 v201, v159, v5
	ds_bpermute_b32 v202, v159, v6
	ds_bpermute_b32 v203, v159, v7
	s_waitcnt lgkmcnt(0)
	v_mul_f32_e32 v188, v84, v188
	v_cndmask_b32_e64 v188, v188, -v188, s[4:5]
	v_fma_f32 v0, v0, v235, v188
	v_mul_f32_e32 v189, v85, v189
	v_cndmask_b32_e64 v189, v189, -v189, s[4:5]
	v_fma_f32 v1, v1, v236, v189
	v_mul_f32_e32 v192, v86, v192
	v_cndmask_b32_e64 v192, v192, -v192, s[4:5]
	v_fma_f32 v2, v2, v237, v192
	v_mul_f32_e32 v193, v87, v193
	v_cndmask_b32_e64 v193, v193, -v193, s[4:5]
	v_fma_f32 v3, v3, v238, v193
	v_mul_f32_e32 v200, v88, v200
	v_cndmask_b32_e64 v200, v200, -v200, s[4:5]
	v_fma_f32 v4, v4, v239, v200
	v_mul_f32_e32 v201, v89, v201
	v_cndmask_b32_e64 v201, v201, -v201, s[4:5]
	v_fma_f32 v5, v5, v240, v201
	v_mul_f32_e32 v202, v74, v202
	v_cndmask_b32_e64 v202, v202, -v202, s[4:5]
	v_fma_f32 v6, v6, v241, v202
	v_mul_f32_e32 v203, v75, v203
	v_cndmask_b32_e64 v203, v203, -v203, s[4:5]
	v_fma_f32 v7, v7, v242, v203
	ds_bpermute_b32 v188, v159, v8
	ds_bpermute_b32 v189, v159, v9
	ds_bpermute_b32 v192, v159, v10
	ds_bpermute_b32 v193, v159, v11
	ds_bpermute_b32 v200, v159, v12
	ds_bpermute_b32 v201, v159, v13
	ds_bpermute_b32 v202, v159, v14
	ds_bpermute_b32 v203, v159, v15
	s_waitcnt lgkmcnt(0)
	v_mul_f32_e32 v188, v76, v188
	v_cndmask_b32_e64 v188, v188, -v188, s[4:5]
	v_fma_f32 v8, v8, v243, v188
	v_mul_f32_e32 v189, v77, v189
	v_cndmask_b32_e64 v189, v189, -v189, s[4:5]
	v_fma_f32 v9, v9, v244, v189
	v_mul_f32_e32 v192, v78, v192
	v_cndmask_b32_e64 v192, v192, -v192, s[4:5]
	v_fma_f32 v10, v10, v245, v192
	v_mul_f32_e32 v193, v80, v193
	v_cndmask_b32_e64 v193, v193, -v193, s[4:5]
	v_fma_f32 v11, v11, v246, v193
	v_mul_f32_e32 v200, v81, v200
	v_cndmask_b32_e64 v200, v200, -v200, s[4:5]
	v_fma_f32 v12, v12, v247, v200
	v_mul_f32_e32 v201, v82, v201
	v_cndmask_b32_e64 v201, v201, -v201, s[4:5]
	v_fma_f32 v13, v13, v248, v201
	v_mul_f32_e32 v202, v156, v202
	v_cndmask_b32_e64 v202, v202, -v202, s[4:5]
	v_fma_f32 v14, v14, v249, v202
	v_mul_f32_e32 v203, v157, v203
	v_cndmask_b32_e64 v203, v203, -v203, s[4:5]
	v_fma_f32 v15, v15, v250, v203
	v_cvt_pk_bf16_f32 v96, v32, v33
	ds_write_b16 v90, v96
	ds_write_b16_d16_hi v90, v96 offset:144
	v_cvt_pk_bf16_f32 v97, v34, v35
	ds_write_b16 v90, v97 offset:288
	ds_write_b16_d16_hi v90, v97 offset:432
	v_cvt_pk_bf16_f32 v98, v36, v37
	ds_write_b16 v90, v98 offset:1152
	ds_write_b16_d16_hi v90, v98 offset:1296
	v_cvt_pk_bf16_f32 v99, v38, v39
	ds_write_b16 v90, v99 offset:1440
	ds_write_b16_d16_hi v90, v99 offset:1584
	v_cvt_pk_bf16_f32 v100, v40, v41
	ds_write_b16 v90, v100 offset:2304
	ds_write_b16_d16_hi v90, v100 offset:2448
	v_cvt_pk_bf16_f32 v101, v42, v43
	ds_write_b16 v90, v101 offset:2592
	ds_write_b16_d16_hi v90, v101 offset:2736
	v_cvt_pk_bf16_f32 v102, v44, v45
	ds_write_b16 v90, v102 offset:3456
	ds_write_b16_d16_hi v90, v102 offset:3600
	v_cvt_pk_bf16_f32 v103, v46, v47
	ds_write_b16 v90, v103 offset:3744
	ds_write_b16_d16_hi v90, v103 offset:3888
	v_cvt_pk_bf16_f32 v104, v48, v49
	ds_write_b16 v90, v104 offset:64
	ds_write_b16_d16_hi v90, v104 offset:208
	v_cvt_pk_bf16_f32 v105, v50, v51
	ds_write_b16 v90, v105 offset:352
	ds_write_b16_d16_hi v90, v105 offset:496
	v_cvt_pk_bf16_f32 v106, v52, v53
	ds_write_b16 v90, v106 offset:1216
	ds_write_b16_d16_hi v90, v106 offset:1360
	v_cvt_pk_bf16_f32 v107, v54, v55
	ds_write_b16 v90, v107 offset:1504
	ds_write_b16_d16_hi v90, v107 offset:1648
	v_cvt_pk_bf16_f32 v108, v56, v57
	ds_write_b16 v90, v108 offset:2368
	ds_write_b16_d16_hi v90, v108 offset:2512
	v_cvt_pk_bf16_f32 v109, v58, v59
	ds_write_b16 v90, v109 offset:2656
	ds_write_b16_d16_hi v90, v109 offset:2800
	v_cvt_pk_bf16_f32 v110, v60, v61
	ds_write_b16 v90, v110 offset:3520
	ds_write_b16_d16_hi v90, v110 offset:3664
	v_cvt_pk_bf16_f32 v111, v62, v63
	ds_write_b16 v90, v111 offset:3808
	ds_write_b16_d16_hi v90, v111 offset:3952
	v_cvt_pk_bf16_f32 v112, v16, v17
	ds_write_b16 v90, v112 offset:4608
	ds_write_b16_d16_hi v90, v112 offset:4752
	v_cvt_pk_bf16_f32 v113, v18, v19
	ds_write_b16 v90, v113 offset:4896
	ds_write_b16_d16_hi v90, v113 offset:5040
	v_cvt_pk_bf16_f32 v114, v20, v21
	ds_write_b16 v90, v114 offset:5760
	ds_write_b16_d16_hi v90, v114 offset:5904
	v_cvt_pk_bf16_f32 v115, v22, v23
	ds_write_b16 v90, v115 offset:6048
	ds_write_b16_d16_hi v90, v115 offset:6192
	v_cvt_pk_bf16_f32 v116, v24, v25
	ds_write_b16 v90, v116 offset:6912
	ds_write_b16_d16_hi v90, v116 offset:7056
	v_cvt_pk_bf16_f32 v117, v26, v27
	ds_write_b16 v90, v117 offset:7200
	ds_write_b16_d16_hi v90, v117 offset:7344
	v_cvt_pk_bf16_f32 v118, v28, v29
	ds_write_b16 v90, v118 offset:8064
	ds_write_b16_d16_hi v90, v118 offset:8208
	v_cvt_pk_bf16_f32 v119, v30, v31
	ds_write_b16 v90, v119 offset:8352
	ds_write_b16_d16_hi v90, v119 offset:8496
	v_cvt_pk_bf16_f32 v120, v0, v1
	ds_write_b16 v90, v120 offset:4672
	ds_write_b16_d16_hi v90, v120 offset:4816
	v_cvt_pk_bf16_f32 v121, v2, v3
	ds_write_b16 v90, v121 offset:4960
	ds_write_b16_d16_hi v90, v121 offset:5104
	v_cvt_pk_bf16_f32 v122, v4, v5
	ds_write_b16 v90, v122 offset:5824
	ds_write_b16_d16_hi v90, v122 offset:5968
	v_cvt_pk_bf16_f32 v123, v6, v7
	ds_write_b16 v90, v123 offset:6112
	ds_write_b16_d16_hi v90, v123 offset:6256
	v_cvt_pk_bf16_f32 v124, v8, v9
	ds_write_b16 v90, v124 offset:6976
	ds_write_b16_d16_hi v90, v124 offset:7120
	v_cvt_pk_bf16_f32 v125, v10, v11
	ds_write_b16 v90, v125 offset:7264
	ds_write_b16_d16_hi v90, v125 offset:7408
	v_cvt_pk_bf16_f32 v126, v12, v13
	ds_write_b16 v90, v126 offset:8128
	ds_write_b16_d16_hi v90, v126 offset:8272
	v_cvt_pk_bf16_f32 v127, v14, v15
	ds_write_b16 v90, v127 offset:8416
	ds_write_b16_d16_hi v90, v127 offset:8560
	s_waitcnt lgkmcnt(0)
	ds_read_b128 v[96:99], v94
	ds_read_b128 v[100:103], v94 offset:1152
	ds_read_b128 v[104:107], v94 offset:2304
	ds_read_b128 v[108:111], v94 offset:3456
	ds_read_b128 v[112:115], v94 offset:4608
	ds_read_b128 v[116:119], v94 offset:5760
	ds_read_b128 v[120:123], v94 offset:6912
	ds_read_b128 v[124:127], v94 offset:8064
	s_waitcnt lgkmcnt(7)
	global_store_dwordx4 v95, v[96:99], s[32:33] offset:128
	s_add_u32 s32, s32, 12288
	s_addc_u32 s33, s33, 0
	s_waitcnt lgkmcnt(6)
	global_store_dwordx4 v95, v[100:103], s[32:33] offset:128
	s_add_u32 s32, s32, 12288
	s_addc_u32 s33, s33, 0
	s_waitcnt lgkmcnt(5)
	global_store_dwordx4 v95, v[104:107], s[32:33] offset:128
	s_add_u32 s32, s32, 12288
	s_addc_u32 s33, s33, 0
	s_waitcnt lgkmcnt(4)
	global_store_dwordx4 v95, v[108:111], s[32:33] offset:128
	s_add_u32 s32, s32, 12288
	s_addc_u32 s33, s33, 0
	s_waitcnt lgkmcnt(3)
	global_store_dwordx4 v95, v[112:115], s[32:33] offset:128
	s_add_u32 s32, s32, 12288
	s_addc_u32 s33, s33, 0
	s_waitcnt lgkmcnt(2)
	global_store_dwordx4 v95, v[116:119], s[32:33] offset:128
	s_add_u32 s32, s32, 12288
	s_addc_u32 s33, s33, 0
	s_waitcnt lgkmcnt(1)
	global_store_dwordx4 v95, v[120:123], s[32:33] offset:128
	s_add_u32 s32, s32, 12288
	s_addc_u32 s33, s33, 0
	s_waitcnt lgkmcnt(0)
	global_store_dwordx4 v95, v[124:127], s[32:33] offset:128
	s_movk_i32 s34, 0x3fff
	s_branch .LBB0_1638
